# filtergen layer 3 on f32 MFMA (v_mfma_f32_32x32x2_f32), per-layer MLP vectors hoisted out of the item loop
# speedup vs baseline: 1.0264x; 1.0264x over previous
; __device__ __forceinline__ float2 twid_precise(float turns) { float s_, c_; sincospif(2.0f * turns, &s_, &c_); return make_float2(c_, s_); }
; __device__ __forceinline__ int otid(int wv) { unsigned z = 0; asm volatile("" : "+v"(z)); int t = wv * 64 + (int)__builtin_amdgcn_mbcnt_hi(~0u, __builtin_amdgcn_mbcnt_lo(~0u, z)); asm volatile("" : "+v"(t)); return t; }
; __device__ __forceinline__ int obid() { int b = blockIdx.x; asm volatile("" : "+s"(b)); return b; }
; __device__ __forceinline__ int ogrid() { int g = gridDim.x; asm volatile("" : "+s"(g)); return g; }
; __device__ __forceinline__ void ph_filtergen(KP p, int l, unsigned char* sm, int wv) {
;     ...
;     const int tid = otid(wv), wid = tid >> 6, lane = tid & 63;
;     const float* b1 = p->fb1 + l * 64; const float* f1 = p->ffr1 + l * 64;
;     const float* b2 = p->fb2 + l * 64; const float* f2 = p->ffr2 + l * 64;
;     const float* w3 = p->fw3 + (size_t)l * 65536; const float* hb = p->hbias + l * 512;
;     __syncthreads();
;     for (int i = tid; i < 33 * 64; i += 512) w1s[i] = p->fw1[l * 33 * 64 + i];
;     for (int i = tid; i < 64 * 64; i += 512) w2s[i] = p->fw2[l * 4096 + i];
;     for (int item = obid(); item < 384; item += ogrid()) {
;         const int L = item < 256 ? LP : LSQ, n0 = (item < 256 ? item : item - 256) * 64;
;         bf16_t* kf = p->X + (item < 256 ? 0 : 16777216);
;         __syncthreads();
;         {
;             const int n = n0 + lane;
;             const float w = 2.0f * (float)n / (float)L;
; #pragma unroll
;             for (int q = 0; q < 2; ++q) {
;                 const int b = wid * 2 + q;
;                 const float f = 1e-4f + (float)b * 0.9999933333333334f;
;                 const float ht = f * w, red = ht - 2.0f * rintf(0.5f * ht);
;                 const float2 cs = twid_precise(0.5f * red);
;                 zf[lane * 34 + 1 + b] = cs.x; zf[lane * 34 + 17 + b] = -cs.y;
;             }
;             if (wid == 0) zf[lane * 34] = (float)n / (float)(L - 1);
;         }
;         __syncthreads();
;         {
;             float a[8];
; #pragma unroll
;             for (int i = 0; i < 8; ++i) a[i] = b1[wid * 8 + i];
.LBB0_881:
	s_or_b64 exec, exec, s[12:13]
	v_readlane_b32 s28, v254, 0
	s_mov_b32 s32, s28
	s_cmpk_gt_i32 s32, 0x2ff
	s_cbranch_scc1 .LBB0_905
	v_readlane_b32 s13, v254, 24
	s_lshl_b32 s12, s13, 8
	s_add_u32 s8, s8, s12
	s_addc_u32 s9, s9, 0
	s_waitcnt lgkmcnt(0)
	s_add_u32 s14, s10, s12
	s_addc_u32 s15, s11, 0
	s_add_u32 s0, s0, s12
	s_addc_u32 s1, s1, 0
	s_add_u32 s16, s2, s12
	s_addc_u32 s17, s3, 0
	s_lshl_b32 s2, s13, 18
	s_add_u32 s2, s4, s2
	s_addc_u32 s3, s5, 0
	s_lshl_b32 s4, s13, 11
	s_add_u32 s10, s6, s4
	v_readlane_b32 s4, v254, 22
	v_ashrrev_i32_e32 v0, 6, v18
	v_readlane_b32 s5, v254, 23
	v_and_b32_e32 v19, 63, v18
	s_load_dwordx2 s[12:13], s[4:5], 0xf0
	v_lshlrev_b32_e32 v3, 1, v0
	s_movk_i32 s4, 0x88
	v_lshlrev_b32_e32 v2, 3, v0
	v_mad_u32_u24 v31, v19, s4, 0
	v_or_b32_e32 v5, 1, v3
	v_cvt_f32_i32_e32 v4, v3
	v_ashrrev_i32_e32 v3, 31, v2
	v_add_u32_e32 v88, v31, v2
	v_lshlrev_b64 v[2:3], 2, v[2:3]
	s_addc_u32 s11, s7, 0
	v_lshl_add_u64 v[26:27], s[0:1], 0, v[2:3]
	s_add_i32 s0, 0, 0x10800
	v_lshlrev_b32_e32 v0, 5, v0
	v_lshl_add_u32 v30, v19, 2, s0
	v_readlane_b32 s0, v254, 8
	v_mul_u32_u24_e32 v6, 0x88, v19
	v_mul_u32_u24_e32 v7, 0x7c, v19
	v_add_u32_e32 v89, s0, v0
	s_add_i32 s0, 0, 0x2200
	v_ashrrev_i32_e32 v8, 3, v18
	v_cvt_f32_i32_e32 v5, v5
	v_add3_u32 v90, v6, v7, s0
	v_readlane_b32 s0, v254, 9
	v_add3_u32 v86, v31, v7, v0
	v_lshl_add_u64 v[22:23], s[8:9], 0, v[2:3]
	v_add_u32_e32 v91, s0, v0
	v_lshrrev_b32_e32 v0, 5, v8
	s_movk_i32 s0, 0x2200
	v_lshl_add_u64 v[24:25], s[14:15], 0, v[2:3]
	v_lshl_add_u64 v[28:29], s[16:17], 0, v[2:3]
	v_mul_lo_u32 v2, v0, s0
	v_readlane_b32 s0, v254, 10
	v_mul_u32_u24_sdwa v9, v18, s87 dst_sel:DWORD dst_unused:UNUSED_PAD src0_sel:BYTE_0 src1_sel:DWORD
	s_mov_b32 s18, 0x3f7fff90
	v_mov_b32_e32 v10, 0x38d1b717
	v_add_u32_e32 v92, s0, v2
	v_lshlrev_b32_e32 v0, 7, v0
	v_readlane_b32 s0, v254, 11
	v_cmp_gt_u32_e64 s[4:5], 64, v18
	v_mad_u32_u24 v87, v19, 12, v86
	v_cmp_gt_i32_e64 s[6:7], s97, v18
	v_pk_fma_f32 v[20:21], v[4:5], s[18:19], v[10:11] op_sel_hi:[1,0,0]
	v_add3_u32 v93, v9, v0, s0
	global_load_dwordx4 v[144:147], v[22:23], off
	global_load_dwordx4 v[148:151], v[22:23], off offset:16
	global_load_dwordx4 v[152:155], v[24:25], off
	global_load_dwordx4 v[156:159], v[24:25], off offset:16
	global_load_dwordx4 v[160:163], v[26:27], off
	global_load_dwordx4 v[164:167], v[26:27], off offset:16
	global_load_dwordx4 v[168:171], v[28:29], off
	global_load_dwordx4 v[172:175], v[28:29], off offset:16
	s_waitcnt vmcnt(0)
	s_branch .LBB0_884

; __device__ __forceinline__ void ph_filtergen(KP p, int l, unsigned char* sm, int wv) {
;     ...
;         {
;             float a[8];
; #pragma unroll
;             for (int i = 0; i < 8; ++i) a[i] = b1[wid * 8 + i];
; #pragma unroll 3
;             for (int f = 0; f < 33; ++f) {
;                 const float zv = zf[lane * 34 + f];
;                 const f32x4 w0 = *(const f32x4*)(w1s + f * 64 + wid * 8), w1v = *(const f32x4*)(w1s + f * 64 + wid * 8 + 4);
;                 a[0] += zv * w0.x; a[1] += zv * w0.y; a[2] += zv * w0.z; a[3] += zv * w0.w; a[4] += zv * w1v.x; a[5] += zv * w1v.y; a[6] += zv * w1v.z; a[7] += zv * w1v.w;
;             }
; #pragma unroll
;             for (int i = 0; i < 8; ++i) h1[lane * 65 + wid * 8 + i] = sinpif(f1[wid * 8 + i] * a[i] * 0.3183098861837907f);
.LBB0_886:
	s_or_b64 exec, exec, s[0:1]
	s_waitcnt lgkmcnt(0)
	s_barrier
	v_mov_b32_e32 v10, v144
	v_mov_b32_e32 v11, v145
	v_mov_b32_e32 v12, v146
	v_mov_b32_e32 v13, v147
	v_mov_b32_e32 v2, v148
	v_mov_b32_e32 v3, v149
	v_mov_b32_e32 v4, v150
	v_mov_b32_e32 v5, v151
	s_mov_b32 s0, 0
	v_mov_b32_e32 v6, v89
.LBB0_887:
	v_add_u32_e32 v7, s0, v31
	ds_read2_b32 v[38:39], v7 offset1:1
	ds_read_b128 v[14:17], v6
	ds_read_b128 v[34:37], v6 offset:16
	s_add_i32 s0, s0, 12
	s_cmpk_eq_i32 s0, 0x84
	s_waitcnt lgkmcnt(1)
	v_pk_fma_f32 v[14:15], v[38:39], v[14:15], v[10:11] op_sel_hi:[0,1,1]
	v_pk_fma_f32 v[12:13], v[38:39], v[16:17], v[12:13] op_sel_hi:[0,1,1]
	s_waitcnt lgkmcnt(0)
	v_pk_fma_f32 v[16:17], v[38:39], v[34:35], v[2:3] op_sel_hi:[0,1,1]
	v_pk_fma_f32 v[34:35], v[38:39], v[36:37], v[4:5] op_sel_hi:[0,1,1]
	ds_read_b128 v[2:5], v6 offset:256
	ds_read_b128 v[8:11], v6 offset:272
	s_waitcnt lgkmcnt(1)
	v_pk_fma_f32 v[36:37], v[38:39], v[2:3], v[14:15] op_sel:[1,0,0]
	v_pk_fma_f32 v[12:13], v[38:39], v[4:5], v[12:13] op_sel:[1,0,0]
	s_waitcnt lgkmcnt(0)
	v_pk_fma_f32 v[8:9], v[38:39], v[8:9], v[16:17] op_sel:[1,0,0]
	v_pk_fma_f32 v[34:35], v[38:39], v[10:11], v[34:35] op_sel:[1,0,0]
	ds_read_b32 v38, v7 offset:8
	ds_read_b128 v[2:5], v6 offset:512
	ds_read_b128 v[14:17], v6 offset:528
	v_add_u32_e32 v6, 0x300, v6
	s_waitcnt lgkmcnt(1)
	v_pk_fma_f32 v[10:11], v[38:39], v[2:3], v[36:37] op_sel_hi:[0,1,1]
	v_pk_fma_f32 v[12:13], v[38:39], v[4:5], v[12:13] op_sel_hi:[0,1,1]
	s_waitcnt lgkmcnt(0)
	v_pk_fma_f32 v[2:3], v[38:39], v[14:15], v[8:9] op_sel_hi:[0,1,1]
	v_pk_fma_f32 v[4:5], v[38:39], v[16:17], v[34:35] op_sel_hi:[0,1,1]
	s_cbranch_scc0 .LBB0_887
	v_mov_b32_e32 v6, v156
	v_mov_b32_e32 v7, v157
	v_mov_b32_e32 v8, v158
	v_mov_b32_e32 v9, v159
	v_mov_b32_e32 v14, v152
	v_mov_b32_e32 v15, v153
	v_mov_b32_e32 v16, v154
	v_mov_b32_e32 v17, v155
	s_mov_b32 s18, 0x3ea2f983
	s_mov_b32 s36, 0x3e75aa41
	s_mov_b32 s38, 0x40234736
	s_mov_b32 s40, 0xc0a55e0e
	s_mov_b32 s42, 0x40490fdb
	s_mov_b32 s44, 0x3d4be544
	s_mov_b32 s46, 0xbfaad1da
	s_mov_b32 s48, 0x4081e0d3
	s_mov_b32 s50, 0xc09de9e6
	s_mov_b32 s15, 0
	v_pk_mul_f32 v[2:3], v[2:3], v[6:7]
	v_pk_mul_f32 v[10:11], v[10:11], v[14:15]
	v_pk_mul_f32 v[12:13], v[12:13], v[16:17]
	v_pk_mul_f32 v[34:35], v[10:11], s[18:19] op_sel_hi:[1,0]
	v_pk_mul_f32 v[12:13], v[12:13], s[18:19] op_sel_hi:[1,0]
	v_and_b32_e32 v37, 0x7fffffff, v35
	v_and_b32_e32 v36, 0x7fffffff, v34
	v_pk_mul_f32 v[10:11], v[36:37], 0.5 op_sel_hi:[1,0]
	v_cmp_gt_f32_e64 s[16:17], |v35|, 1.0
	v_floor_f32_e32 v14, v10
	v_floor_f32_e32 v15, v11
	v_sub_f32_e32 v14, v10, v14
	v_sub_f32_e32 v15, v11, v15
	v_min_f32_e32 v14, 0x3f7fffff, v14
	v_min_f32_e32 v15, 0x3f7fffff, v15
	v_cmp_u_f32_e32 vcc, v10, v10
	v_cmp_u_f32_e64 s[0:1], v11, v11
	v_xor_b32_e32 v37, v37, v35
	v_cndmask_b32_e32 v14, v14, v10, vcc
	v_cndmask_b32_e64 v15, v15, v11, s[0:1]
	v_cmp_class_f32_e32 vcc, v11, v239
	v_cmp_class_f32_e64 s[0:1], v10, v239
	v_pk_add_f32 v[10:11], v[14:15], v[14:15]
	v_xor_b32_e32 v36, v36, v34
	v_cndmask_b32_e64 v10, v10, 0, s[0:1]
	v_cndmask_b32_e64 v11, v11, 0, vcc
	v_cmp_gt_f32_e64 s[0:1], |v34|, 1.0
	v_cndmask_b32_e64 v11, |v35|, v11, s[16:17]
	v_add_f32_e32 v15, v11, v11
	v_cndmask_b32_e64 v10, |v34|, v10, s[0:1]
	v_add_f32_e32 v14, v10, v10
	v_rndne_f32_e32 v14, v14
	v_rndne_f32_e32 v15, v15
	v_pk_fma_f32 v[38:39], v[14:15], -0.5, v[10:11] op_sel_hi:[1,0,1]
	s_mov_b32 s0, 0xbf1f24be
	v_pk_mul_f32 v[40:41], v[38:39], v[38:39]
	v_mov_b64_e32 v[10:11], s[0:1]
	v_cvt_i32_f32_e32 v33, v15
	v_cvt_i32_f32_e32 v44, v14
	v_pk_fma_f32 v[14:15], v[40:41], s[36:37], v[10:11] op_sel_hi:[1,0,0]
	v_pk_mul_f32 v[42:43], v[38:39], v[40:41]
	v_pk_fma_f32 v[14:15], v[40:41], v[14:15], s[38:39] op_sel_hi:[1,1,0]
	s_mov_b32 s0, 0x3e642e9d
	v_pk_fma_f32 v[14:15], v[40:41], v[14:15], s[40:41] op_sel_hi:[1,1,0]
	v_and_b32_e32 v17, 0x7fffffff, v13
	v_pk_mul_f32 v[14:15], v[42:43], v[14:15]
	v_and_b32_e32 v16, 0x7fffffff, v12
	v_pk_fma_f32 v[38:39], v[38:39], s[42:43], v[14:15] op_sel_hi:[1,0,1]
	v_mov_b64_e32 v[14:15], s[0:1]
	v_pk_fma_f32 v[42:43], v[40:41], s[44:45], v[14:15] op_sel_hi:[1,0,0]
	v_cmp_gt_f32_e64 s[16:17], |v13|, 1.0
	v_pk_fma_f32 v[42:43], v[40:41], v[42:43], s[46:47] op_sel_hi:[1,1,0]
	v_pk_mul_f32 v[2:3], v[2:3], s[18:19] op_sel_hi:[1,0]
	v_pk_fma_f32 v[42:43], v[40:41], v[42:43], s[48:49] op_sel_hi:[1,1,0]
	v_and_b32_e32 v7, 0x7fffffff, v3
	v_pk_fma_f32 v[42:43], v[40:41], v[42:43], s[50:51] op_sel_hi:[1,1,0]
	v_and_b32_e32 v6, 0x7fffffff, v2
	v_pk_fma_f32 v[40:41], v[40:41], v[42:43], 1.0 op_sel_hi:[1,1,0]
	v_and_b32_e32 v43, 1, v44
	v_cmp_eq_u32_e32 vcc, 0, v43
	v_and_b32_e32 v42, 1, v33
	v_lshlrev_b32_e32 v33, 30, v33
	v_cndmask_b32_e32 v38, v40, v38, vcc
	v_lshlrev_b32_e32 v40, 30, v44
	v_cmp_eq_u32_e64 s[0:1], 0, v42
	v_and_b32_e32 v33, 0x80000000, v33
	v_and_b32_e32 v40, 0x80000000, v40
	v_cndmask_b32_e64 v39, v41, v39, s[0:1]
	v_xor_b32_e32 v33, v37, v33
	v_xor_b32_e32 v36, v36, v40
	v_xor_b32_e32 v33, v33, v39
	v_xor_b32_e32 v36, v36, v38
	v_cmp_class_f32_e32 vcc, v34, v242
	v_cmp_class_f32_e64 s[0:1], v35, v242
	v_add_u32_e32 v35, 0x2200, v86
	v_cndmask_b32_e32 v34, v204, v36, vcc
	v_cndmask_b32_e64 v33, v204, v33, s[0:1]
	ds_write2_b32 v35, v34, v33 offset1:1
	v_pk_mul_f32 v[34:35], v[16:17], 0.5 op_sel_hi:[1,0]
	v_xor_b32_e32 v17, v17, v13
	v_floor_f32_e32 v33, v34
	v_floor_f32_e32 v36, v35
	v_sub_f32_e32 v33, v34, v33
	v_sub_f32_e32 v36, v35, v36
	v_min_f32_e32 v33, 0x3f7fffff, v33
	v_min_f32_e32 v36, 0x3f7fffff, v36
	v_cmp_u_f32_e32 vcc, v34, v34
	v_cmp_u_f32_e64 s[0:1], v35, v35
	v_xor_b32_e32 v16, v16, v12
	s_nop 0
; __device__ __forceinline__ void ph_filtergen(KP p, int l, unsigned char* sm, int wv) {
;     ...
;             for (int i = 0; i < 8; ++i) h1[lane * 65 + wid * 8 + i] = sinpif(f1[wid * 8 + i] * a[i] * 0.3183098861837907f);
	v_cndmask_b32_e64 v37, v36, v35, s[0:1]
	v_cndmask_b32_e32 v36, v33, v34, vcc
	v_cmp_class_f32_e32 vcc, v35, v239
	v_cmp_class_f32_e64 s[0:1], v34, v239
	v_pk_add_f32 v[34:35], v[36:37], v[36:37]
	s_nop 0
	v_cndmask_b32_e64 v33, v34, 0, s[0:1]
	v_cndmask_b32_e64 v34, v35, 0, vcc
	v_cmp_gt_f32_e64 s[0:1], |v12|, 1.0
	v_cndmask_b32_e64 v35, |v13|, v34, s[16:17]
	v_cmp_gt_f32_e64 s[16:17], |v3|, 1.0
	v_cndmask_b32_e64 v34, |v12|, v33, s[0:1]
	v_add_f32_e32 v33, v34, v34
	v_rndne_f32_e32 v36, v33
	v_add_f32_e32 v33, v35, v35
	v_rndne_f32_e32 v37, v33
	v_pk_fma_f32 v[34:35], v[36:37], -0.5, v[34:35] op_sel_hi:[1,0,1]
	v_cvt_i32_f32_e32 v33, v37
	v_cvt_i32_f32_e32 v42, v36
	v_pk_mul_f32 v[36:37], v[34:35], v[34:35]
	s_nop 0
	v_pk_fma_f32 v[38:39], v[36:37], s[36:37], v[10:11] op_sel_hi:[1,0,0]
	v_pk_mul_f32 v[40:41], v[34:35], v[36:37]
	v_pk_fma_f32 v[38:39], v[36:37], v[38:39], s[38:39] op_sel_hi:[1,1,0]
	s_nop 0
	v_pk_fma_f32 v[38:39], v[36:37], v[38:39], s[40:41] op_sel_hi:[1,1,0]
	s_nop 0
	v_pk_mul_f32 v[38:39], v[40:41], v[38:39]
	s_nop 0
	v_pk_fma_f32 v[34:35], v[34:35], s[42:43], v[38:39] op_sel_hi:[1,0,1]
	v_pk_fma_f32 v[38:39], v[36:37], s[44:45], v[14:15] op_sel_hi:[1,0,0]
	s_nop 0
	v_pk_fma_f32 v[38:39], v[36:37], v[38:39], s[46:47] op_sel_hi:[1,1,0]
	s_nop 0
	v_pk_fma_f32 v[38:39], v[36:37], v[38:39], s[48:49] op_sel_hi:[1,1,0]
	s_nop 0
	v_pk_fma_f32 v[38:39], v[36:37], v[38:39], s[50:51] op_sel_hi:[1,1,0]
	s_nop 0
	v_pk_fma_f32 v[36:37], v[36:37], v[38:39], 1.0 op_sel_hi:[1,1,0]
	v_and_b32_e32 v39, 1, v42
	v_cmp_eq_u32_e32 vcc, 0, v39
	v_and_b32_e32 v38, 1, v33
	v_lshlrev_b32_e32 v33, 30, v33
	v_cndmask_b32_e32 v34, v36, v34, vcc
	v_lshlrev_b32_e32 v36, 30, v42
	v_cmp_eq_u32_e64 s[0:1], 0, v38
	v_and_b32_e32 v33, 0x80000000, v33
	v_and_b32_e32 v36, 0x80000000, v36
	v_cndmask_b32_e64 v35, v37, v35, s[0:1]
	v_xor_b32_e32 v17, v17, v33
	v_xor_b32_e32 v16, v16, v36
	v_xor_b32_e32 v17, v17, v35
	v_xor_b32_e32 v16, v16, v34
	v_cmp_class_f32_e32 vcc, v12, v242
	v_cmp_class_f32_e64 s[0:1], v13, v242
	s_nop 0
	v_cndmask_b32_e32 v13, v204, v16, vcc
	v_cndmask_b32_e64 v12, v204, v17, s[0:1]
	v_add_u32_e32 v16, 0x2208, v86
	ds_write2_b32 v16, v13, v12 offset1:1
	v_pk_mul_f32 v[12:13], v[6:7], 0.5 op_sel_hi:[1,0]
	v_xor_b32_e32 v7, v7, v3
	v_floor_f32_e32 v16, v12
	v_floor_f32_e32 v17, v13
	v_sub_f32_e32 v16, v12, v16
	v_sub_f32_e32 v17, v13, v17
	v_min_f32_e32 v16, 0x3f7fffff, v16
	v_min_f32_e32 v17, 0x3f7fffff, v17
	v_cmp_u_f32_e32 vcc, v12, v12
	v_cmp_u_f32_e64 s[0:1], v13, v13
	v_xor_b32_e32 v6, v6, v2
	v_cndmask_b32_e32 v16, v16, v12, vcc
	v_cndmask_b32_e64 v17, v17, v13, s[0:1]
	v_cmp_class_f32_e32 vcc, v13, v239
	v_cmp_class_f32_e64 s[0:1], v12, v239
	v_pk_add_f32 v[12:13], v[16:17], v[16:17]
	s_nop 0
	v_cndmask_b32_e64 v12, v12, 0, s[0:1]
	v_cndmask_b32_e64 v13, v13, 0, vcc
	v_cmp_gt_f32_e64 s[0:1], |v2|, 1.0
	v_cndmask_b32_e64 v13, |v3|, v13, s[16:17]
	v_add_f32_e32 v17, v13, v13
	v_cndmask_b32_e64 v12, |v2|, v12, s[0:1]
	v_add_f32_e32 v16, v12, v12
	v_rndne_f32_e32 v16, v16
	v_rndne_f32_e32 v17, v17
	v_pk_fma_f32 v[12:13], v[16:17], -0.5, v[12:13] op_sel_hi:[1,0,1]
	v_cvt_i32_f32_e32 v33, v17
	v_cvt_i32_f32_e32 v38, v16
	v_pk_mul_f32 v[16:17], v[12:13], v[12:13]
	s_nop 0
	v_pk_fma_f32 v[34:35], v[16:17], s[36:37], v[10:11] op_sel_hi:[1,0,0]
	v_pk_mul_f32 v[36:37], v[12:13], v[16:17]
	v_pk_fma_f32 v[34:35], v[16:17], v[34:35], s[38:39] op_sel_hi:[1,1,0]
	s_nop 0
	v_pk_fma_f32 v[34:35], v[16:17], v[34:35], s[40:41] op_sel_hi:[1,1,0]
	s_nop 0
	v_pk_mul_f32 v[34:35], v[36:37], v[34:35]
	s_nop 0
	v_pk_fma_f32 v[12:13], v[12:13], s[42:43], v[34:35] op_sel_hi:[1,0,1]
	v_pk_fma_f32 v[34:35], v[16:17], s[44:45], v[14:15] op_sel_hi:[1,0,0]
	s_nop 0
	v_pk_fma_f32 v[34:35], v[16:17], v[34:35], s[46:47] op_sel_hi:[1,1,0]
	s_nop 0
	v_pk_fma_f32 v[34:35], v[16:17], v[34:35], s[48:49] op_sel_hi:[1,1,0]
	s_nop 0
	v_pk_fma_f32 v[34:35], v[16:17], v[34:35], s[50:51] op_sel_hi:[1,1,0]
	s_nop 0
	v_pk_fma_f32 v[16:17], v[16:17], v[34:35], 1.0 op_sel_hi:[1,1,0]
	v_and_b32_e32 v34, 1, v33
	v_and_b32_e32 v35, 1, v38
	v_cmp_eq_u32_e32 vcc, 0, v35
	v_cmp_eq_u32_e64 s[0:1], 0, v34
	s_nop 0
	v_cndmask_b32_e32 v12, v16, v12, vcc
	v_cndmask_b32_e64 v13, v17, v13, s[0:1]
	v_lshlrev_b32_e32 v16, 30, v33
	v_lshlrev_b32_e32 v17, 30, v38
	v_and_b32_e32 v16, 0x80000000, v16
	v_and_b32_e32 v17, 0x80000000, v17
	v_xor_b32_e32 v7, v7, v16
	v_xor_b32_e32 v6, v6, v17
	v_xor_b32_e32 v7, v7, v13
	v_xor_b32_e32 v6, v6, v12
	v_cmp_class_f32_e32 vcc, v2, v242
	v_cmp_class_f32_e64 s[0:1], v3, v242
	s_nop 0
	v_cndmask_b32_e32 v3, v204, v6, vcc
	v_cndmask_b32_e64 v2, v204, v7, s[0:1]
	v_add_u32_e32 v6, 0x2210, v86
	ds_write2_b32 v6, v3, v2 offset1:1
	v_pk_mul_f32 v[2:3], v[4:5], v[8:9]
	s_nop 0
	v_pk_mul_f32 v[2:3], v[2:3], s[18:19] op_sel_hi:[1,0]
	s_nop 0
	v_and_b32_e32 v5, 0x7fffffff, v3
	v_and_b32_e32 v4, 0x7fffffff, v2
	v_pk_mul_f32 v[6:7], v[4:5], 0.5 op_sel_hi:[1,0]
	v_cmp_gt_f32_e64 s[16:17], |v3|, 1.0
	v_floor_f32_e32 v8, v6
	v_floor_f32_e32 v9, v7
	v_sub_f32_e32 v8, v6, v8
	v_sub_f32_e32 v9, v7, v9
	v_min_f32_e32 v8, 0x3f7fffff, v8
	v_min_f32_e32 v9, 0x3f7fffff, v9
	v_cmp_u_f32_e32 vcc, v6, v6
	v_cmp_u_f32_e64 s[0:1], v7, v7
	v_xor_b32_e32 v5, v5, v3
	v_cndmask_b32_e32 v8, v8, v6, vcc
	v_cndmask_b32_e64 v9, v9, v7, s[0:1]
	v_cmp_class_f32_e32 vcc, v7, v239
	v_cmp_class_f32_e64 s[0:1], v6, v239
	v_pk_add_f32 v[6:7], v[8:9], v[8:9]
	v_xor_b32_e32 v4, v4, v2
	v_cndmask_b32_e64 v6, v6, 0, s[0:1]
	v_cndmask_b32_e64 v7, v7, 0, vcc
	v_cmp_gt_f32_e64 s[0:1], |v2|, 1.0
	v_cndmask_b32_e64 v7, |v3|, v7, s[16:17]
	v_add_f32_e32 v9, v7, v7
	v_cndmask_b32_e64 v6, |v2|, v6, s[0:1]
; __device__ __forceinline__ void ph_filtergen(KP p, int l, unsigned char* sm, int wv) {
;     ...
;             for (int i = 0; i < 8; ++i) h1[lane * 65 + wid * 8 + i] = sinpif(f1[wid * 8 + i] * a[i] * 0.3183098861837907f);
;         }
;         __syncthreads();
;         {
;             float a[8];
; #pragma unroll
;             for (int i = 0; i < 8; ++i) a[i] = b2[wid * 8 + i];
; #pragma unroll 4
;             for (int j = 0; j < 64; ++j) {
;                 const float zv = h1[lane * 65 + j];
;                 const f32x4 w0 = *(const f32x4*)(w2s + j * 64 + wid * 8), w1v = *(const f32x4*)(w2s + j * 64 + wid * 8 + 4);
;                 a[0] += zv * w0.x; a[1] += zv * w0.y; a[2] += zv * w0.z; a[3] += zv * w0.w; a[4] += zv * w1v.x; a[5] += zv * w1v.y; a[6] += zv * w1v.z; a[7] += zv * w1v.w;
;             }
; #pragma unroll
;             for (int i = 0; i < 8; ++i) h2[lane * 68 + wid * 8 + i] = sinpif(f2[wid * 8 + i] * a[i] * 0.3183098861837907f);
	v_add_f32_e32 v8, v6, v6
	v_rndne_f32_e32 v8, v8
	v_rndne_f32_e32 v9, v9
	v_pk_fma_f32 v[6:7], v[8:9], -0.5, v[6:7] op_sel_hi:[1,0,1]
	v_cvt_i32_f32_e32 v16, v9
	v_cvt_i32_f32_e32 v17, v8
	v_pk_mul_f32 v[8:9], v[6:7], v[6:7]
	s_nop 0
	v_pk_fma_f32 v[10:11], v[8:9], s[36:37], v[10:11] op_sel_hi:[1,0,0]
	v_pk_mul_f32 v[12:13], v[6:7], v[8:9]
	v_pk_fma_f32 v[10:11], v[8:9], v[10:11], s[38:39] op_sel_hi:[1,1,0]
	s_nop 0
	v_pk_fma_f32 v[10:11], v[8:9], v[10:11], s[40:41] op_sel_hi:[1,1,0]
	s_nop 0
	v_pk_mul_f32 v[10:11], v[12:13], v[10:11]
	s_nop 0
	v_pk_fma_f32 v[6:7], v[6:7], s[42:43], v[10:11] op_sel_hi:[1,0,1]
	v_pk_fma_f32 v[10:11], v[8:9], s[44:45], v[14:15] op_sel_hi:[1,0,0]
	s_nop 0
	v_pk_fma_f32 v[10:11], v[8:9], v[10:11], s[46:47] op_sel_hi:[1,1,0]
	s_nop 0
	v_pk_fma_f32 v[10:11], v[8:9], v[10:11], s[48:49] op_sel_hi:[1,1,0]
	s_nop 0
	v_pk_fma_f32 v[10:11], v[8:9], v[10:11], s[50:51] op_sel_hi:[1,1,0]
	s_nop 0
	v_pk_fma_f32 v[8:9], v[8:9], v[10:11], 1.0 op_sel_hi:[1,1,0]
	v_and_b32_e32 v10, 1, v16
	v_and_b32_e32 v11, 1, v17
	v_cmp_eq_u32_e32 vcc, 0, v11
	v_cmp_eq_u32_e64 s[0:1], 0, v10
	s_nop 0
	v_cndmask_b32_e32 v6, v8, v6, vcc
	v_cndmask_b32_e64 v7, v9, v7, s[0:1]
	v_lshlrev_b32_e32 v8, 30, v16
	v_lshlrev_b32_e32 v9, 30, v17
	v_and_b32_e32 v8, 0x80000000, v8
	v_and_b32_e32 v9, 0x80000000, v9
	v_xor_b32_e32 v5, v5, v8
	v_xor_b32_e32 v4, v4, v9
	v_xor_b32_e32 v5, v5, v7
	v_xor_b32_e32 v4, v4, v6
	v_cmp_class_f32_e32 vcc, v2, v242
	v_cmp_class_f32_e64 s[0:1], v3, v242
	v_mov_b32_e32 v6, v91
	v_cndmask_b32_e32 v3, v204, v4, vcc
	v_cndmask_b32_e64 v2, v204, v5, s[0:1]
	v_add_u32_e32 v4, 0x2218, v86
	ds_write2_b32 v4, v3, v2 offset1:1
	s_waitcnt lgkmcnt(0)
	s_barrier
	v_mov_b32_e32 v10, v160
	v_mov_b32_e32 v11, v161
	v_mov_b32_e32 v12, v162
	v_mov_b32_e32 v13, v163
	v_mov_b32_e32 v2, v164
	v_mov_b32_e32 v3, v165
	v_mov_b32_e32 v4, v166
	v_mov_b32_e32 v5, v167
.LBB0_889:
	v_add_u32_e32 v7, s15, v90
	ds_read2_b32 v[38:39], v7 offset1:1
	ds_read_b128 v[14:17], v6
	ds_read_b128 v[34:37], v6 offset:16
	s_add_i32 s15, s15, 16
	s_cmpk_eq_i32 s15, 0x100
	s_waitcnt lgkmcnt(1)
	v_pk_fma_f32 v[14:15], v[38:39], v[14:15], v[10:11] op_sel_hi:[0,1,1]
	v_pk_fma_f32 v[12:13], v[38:39], v[16:17], v[12:13] op_sel_hi:[0,1,1]
	s_waitcnt lgkmcnt(0)
	v_pk_fma_f32 v[16:17], v[38:39], v[34:35], v[2:3] op_sel_hi:[0,1,1]
	v_pk_fma_f32 v[34:35], v[38:39], v[36:37], v[4:5] op_sel_hi:[0,1,1]
	ds_read_b128 v[2:5], v6 offset:256
	ds_read_b128 v[8:11], v6 offset:272
	s_waitcnt lgkmcnt(1)
	v_pk_fma_f32 v[14:15], v[38:39], v[2:3], v[14:15] op_sel:[1,0,0]
	v_pk_fma_f32 v[12:13], v[38:39], v[4:5], v[12:13] op_sel:[1,0,0]
	s_waitcnt lgkmcnt(0)
	v_pk_fma_f32 v[16:17], v[38:39], v[8:9], v[16:17] op_sel:[1,0,0]
	v_pk_fma_f32 v[34:35], v[38:39], v[10:11], v[34:35] op_sel:[1,0,0]
	ds_read2_b32 v[36:37], v7 offset0:2 offset1:3
	ds_read_b128 v[2:5], v6 offset:512
	ds_read_b128 v[8:11], v6 offset:528
	s_waitcnt lgkmcnt(1)
	v_pk_fma_f32 v[38:39], v[36:37], v[2:3], v[14:15] op_sel_hi:[0,1,1]
	v_pk_fma_f32 v[12:13], v[36:37], v[4:5], v[12:13] op_sel_hi:[0,1,1]
	s_waitcnt lgkmcnt(0)
	v_pk_fma_f32 v[8:9], v[36:37], v[8:9], v[16:17] op_sel_hi:[0,1,1]
	ds_read_b128 v[2:5], v6 offset:768
	ds_read_b128 v[14:17], v6 offset:784
	v_pk_fma_f32 v[34:35], v[36:37], v[10:11], v[34:35] op_sel_hi:[0,1,1]
	v_add_u32_e32 v6, 0x400, v6
	s_waitcnt lgkmcnt(1)
	v_pk_fma_f32 v[10:11], v[36:37], v[2:3], v[38:39] op_sel:[1,0,0]
	v_pk_fma_f32 v[12:13], v[36:37], v[4:5], v[12:13] op_sel:[1,0,0]
	s_waitcnt lgkmcnt(0)
	v_pk_fma_f32 v[2:3], v[36:37], v[14:15], v[8:9] op_sel:[1,0,0]
	v_pk_fma_f32 v[4:5], v[36:37], v[16:17], v[34:35] op_sel:[1,0,0]
	s_cbranch_scc0 .LBB0_889
	v_mov_b32_e32 v34, v168
	v_mov_b32_e32 v35, v169
	v_mov_b32_e32 v36, v170
	v_mov_b32_e32 v37, v171
	v_mov_b32_e32 v6, v172
	v_mov_b32_e32 v7, v173
	v_mov_b32_e32 v8, v174
	v_mov_b32_e32 v9, v175
	s_mov_b32 s18, 0x3ea2f983
	s_and_b64 s[0:1], s[8:9], exec
	s_mov_b32 s0, 0xbf1f24be
	v_mov_b64_e32 v[14:15], s[0:1]
	s_mov_b32 s0, 0x3e642e9d
	v_mov_b64_e32 v[16:17], s[0:1]
	s_cselect_b32 s0, 0, 0x2000000
	s_add_u32 s16, s12, s0
	s_mov_b32 s36, 0x3e75aa41
	s_mov_b32 s44, 0x3d4be544
	s_mov_b32 s38, 0x40234736
	s_mov_b32 s46, 0xbfaad1da
	s_mov_b32 s40, 0xc0a55e0e
	s_mov_b32 s48, 0x4081e0d3
	s_mov_b32 s50, 0xc09de9e6
	s_mov_b32 s42, 0x40490fdb
	s_addc_u32 s17, s13, 0
	s_and_b32 s31, s32, 1
	s_lshl_b32 s31, s31, 1
	s_mov_b32 s15, s72
	v_pk_mul_f32 v[10:11], v[10:11], v[34:35]
	s_nop 0
	v_pk_mul_f32 v[34:35], v[10:11], s[18:19] op_sel_hi:[1,0]
	v_pk_mul_f32 v[12:13], v[12:13], v[36:37]
	v_and_b32_e32 v37, 0x7fffffff, v35
	v_and_b32_e32 v36, 0x7fffffff, v34
	v_pk_mul_f32 v[10:11], v[12:13], s[18:19] op_sel_hi:[1,0]
	v_pk_mul_f32 v[38:39], v[36:37], 0.5 op_sel_hi:[1,0]
	v_and_b32_e32 v13, 0x7fffffff, v11
	v_and_b32_e32 v12, 0x7fffffff, v10
	v_floor_f32_e32 v41, v39
	v_xor_b32_e32 v33, v37, v35
	v_xor_b32_e32 v48, v36, v34
	v_pk_mul_f32 v[36:37], v[12:13], 0.5 op_sel_hi:[1,0]
	v_floor_f32_e32 v40, v38
	v_sub_f32_e32 v41, v39, v41
	v_floor_f32_e32 v43, v37
	v_sub_f32_e32 v40, v38, v40
	v_min_f32_e32 v41, 0x3f7fffff, v41
	v_cmp_u_f32_e32 vcc, v39, v39
	v_floor_f32_e32 v42, v36
	v_sub_f32_e32 v43, v37, v43
	v_min_f32_e32 v40, 0x3f7fffff, v40
	v_cndmask_b32_e32 v41, v41, v39, vcc
	v_cmp_u_f32_e32 vcc, v38, v38
	v_sub_f32_e32 v42, v36, v42
	v_min_f32_e32 v43, 0x3f7fffff, v43
	v_cndmask_b32_e32 v40, v40, v38, vcc
	v_cmp_u_f32_e32 vcc, v37, v37
	v_min_f32_e32 v42, 0x3f7fffff, v42
	v_pk_add_f32 v[40:41], v[40:41], v[40:41]
	v_cndmask_b32_e32 v43, v43, v37, vcc
	v_cmp_u_f32_e32 vcc, v36, v36
	v_cmp_gt_f32_e64 s[0:1], |v35|, 1.0
	v_xor_b32_e32 v13, v13, v11
; __device__ __forceinline__ void ph_filtergen(KP p, int l, unsigned char* sm, int wv) {
;     ...
;             for (int i = 0; i < 8; ++i) h2[lane * 68 + wid * 8 + i] = sinpif(f2[wid * 8 + i] * a[i] * 0.3183098861837907f);
	v_cndmask_b32_e32 v42, v42, v36, vcc
	v_cmp_class_f32_e32 vcc, v38, v239
	v_pk_add_f32 v[42:43], v[42:43], v[42:43]
	v_pk_mul_f32 v[2:3], v[2:3], v[6:7]
	v_cndmask_b32_e64 v38, v40, 0, vcc
	v_cmp_class_f32_e32 vcc, v39, v239
	v_pk_mul_f32 v[2:3], v[2:3], s[18:19] op_sel_hi:[1,0]
	v_xor_b32_e32 v12, v12, v10
	v_cndmask_b32_e64 v39, v41, 0, vcc
	v_cmp_class_f32_e32 vcc, v36, v239
	v_and_b32_e32 v7, 0x7fffffff, v3
	v_and_b32_e32 v6, 0x7fffffff, v2
	v_cndmask_b32_e64 v40, v42, 0, vcc
	v_cmp_class_f32_e32 vcc, v37, v239
	v_cndmask_b32_e64 v37, |v35|, v39, s[0:1]
	v_cmp_gt_f32_e64 s[0:1], |v34|, 1.0
	v_cndmask_b32_e64 v41, v43, 0, vcc
	v_pk_mul_f32 v[4:5], v[4:5], v[8:9]
	v_cndmask_b32_e64 v36, |v34|, v38, s[0:1]
	v_cmp_gt_f32_e64 s[0:1], |v11|, 1.0
	v_pk_mul_f32 v[4:5], v[4:5], s[18:19] op_sel_hi:[1,0]
	s_lshl_b32 s18, s14, 1
	v_cndmask_b32_e64 v39, |v11|, v41, s[0:1]
	v_cmp_gt_f32_e64 s[0:1], |v10|, 1.0
	v_add_f32_e32 v41, v37, v37
	v_rndne_f32_e32 v41, v41
	v_cndmask_b32_e64 v38, |v10|, v40, s[0:1]
	v_add_f32_e32 v40, v36, v36
	v_rndne_f32_e32 v40, v40
	v_add_f32_e32 v42, v38, v38
	v_add_f32_e32 v43, v39, v39
	v_pk_fma_f32 v[36:37], v[40:41], -0.5, v[36:37] op_sel_hi:[1,0,1]
	v_rndne_f32_e32 v42, v42
	v_rndne_f32_e32 v43, v43
	v_cvt_i32_f32_e32 v49, v41
	v_cvt_i32_f32_e32 v50, v40
	v_pk_mul_f32 v[40:41], v[36:37], v[36:37]
	v_pk_fma_f32 v[38:39], v[42:43], -0.5, v[38:39] op_sel_hi:[1,0,1]
	v_cvt_i32_f32_e32 v51, v43
	v_cvt_i32_f32_e32 v52, v42
	v_pk_fma_f32 v[42:43], v[40:41], s[36:37], v[14:15] op_sel_hi:[1,0,0]
	v_pk_fma_f32 v[46:47], v[40:41], s[44:45], v[16:17] op_sel_hi:[1,0,0]
	v_pk_fma_f32 v[42:43], v[40:41], v[42:43], s[38:39] op_sel_hi:[1,1,0]
	v_pk_fma_f32 v[46:47], v[40:41], v[46:47], s[46:47] op_sel_hi:[1,1,0]
	v_pk_mul_f32 v[44:45], v[36:37], v[40:41]
	v_pk_fma_f32 v[42:43], v[40:41], v[42:43], s[40:41] op_sel_hi:[1,1,0]
	v_pk_fma_f32 v[46:47], v[40:41], v[46:47], s[48:49] op_sel_hi:[1,1,0]
	v_and_b32_e32 v53, 1, v49
	v_lshlrev_b32_e32 v49, 30, v49
	v_pk_mul_f32 v[42:43], v[44:45], v[42:43]
	v_pk_fma_f32 v[44:45], v[40:41], v[46:47], s[50:51] op_sel_hi:[1,1,0]
	v_and_b32_e32 v54, 1, v50
	v_lshlrev_b32_e32 v50, 30, v50
	v_and_b32_e32 v46, 0x80000000, v49
	v_pk_fma_f32 v[36:37], v[36:37], s[42:43], v[42:43] op_sel_hi:[1,0,1]
	v_pk_fma_f32 v[40:41], v[40:41], v[44:45], 1.0 op_sel_hi:[1,1,0]
	v_cmp_eq_u32_e32 vcc, 0, v53
	v_and_b32_e32 v47, 0x80000000, v50
	v_xor_b32_e32 v33, v33, v46
	v_cndmask_b32_e32 v37, v41, v37, vcc
	v_cmp_eq_u32_e32 vcc, 0, v54
	v_xor_b32_e32 v42, v48, v47
	v_xor_b32_e32 v33, v33, v37
	v_cndmask_b32_e32 v36, v40, v36, vcc
	v_cmp_class_f32_e32 vcc, v35, v242
	v_xor_b32_e32 v36, v42, v36
	v_cmp_gt_f32_e64 s[0:1], |v3|, 1.0
	v_cndmask_b32_e32 v35, v204, v33, vcc
	v_cmp_class_f32_e32 vcc, v34, v242
	v_and_b32_e32 v33, 1, v51
	s_nop 0
	v_cndmask_b32_e32 v34, v204, v36, vcc
	v_pk_mul_f32 v[36:37], v[38:39], v[38:39]
	v_cmp_eq_u32_e32 vcc, 0, v33
	v_pk_fma_f32 v[40:41], v[36:37], s[36:37], v[14:15] op_sel_hi:[1,0,0]
	v_pk_mul_f32 v[42:43], v[38:39], v[36:37]
	v_pk_fma_f32 v[40:41], v[36:37], v[40:41], s[38:39] op_sel_hi:[1,1,0]
	s_nop 0
	v_pk_fma_f32 v[40:41], v[36:37], v[40:41], s[40:41] op_sel_hi:[1,1,0]
	s_nop 0
	v_pk_mul_f32 v[40:41], v[42:43], v[40:41]
	s_nop 0
	v_pk_fma_f32 v[38:39], v[38:39], s[42:43], v[40:41] op_sel_hi:[1,0,1]
	v_pk_fma_f32 v[40:41], v[36:37], s[44:45], v[16:17] op_sel_hi:[1,0,0]
	s_nop 0
	v_pk_fma_f32 v[40:41], v[36:37], v[40:41], s[46:47] op_sel_hi:[1,1,0]
	s_nop 0
	v_pk_fma_f32 v[40:41], v[36:37], v[40:41], s[48:49] op_sel_hi:[1,1,0]
	s_nop 0
	v_pk_fma_f32 v[40:41], v[36:37], v[40:41], s[50:51] op_sel_hi:[1,1,0]
	s_nop 0
	v_pk_fma_f32 v[36:37], v[36:37], v[40:41], 1.0 op_sel_hi:[1,1,0]
	v_and_b32_e32 v40, 1, v52
	v_cndmask_b32_e32 v33, v37, v39, vcc
	v_lshlrev_b32_e32 v37, 30, v51
	v_cmp_eq_u32_e32 vcc, 0, v40
	v_and_b32_e32 v37, 0x80000000, v37
	v_xor_b32_e32 v13, v13, v37
	v_cndmask_b32_e32 v36, v36, v38, vcc
	v_lshlrev_b32_e32 v38, 30, v52
	v_and_b32_e32 v38, 0x80000000, v38
	v_xor_b32_e32 v13, v13, v33
	v_cmp_class_f32_e32 vcc, v11, v242
	v_xor_b32_e32 v12, v12, v38
	v_xor_b32_e32 v12, v12, v36
	v_cndmask_b32_e32 v37, v204, v13, vcc
	v_cmp_class_f32_e32 vcc, v10, v242
	v_pk_mul_f32 v[10:11], v[6:7], 0.5 op_sel_hi:[1,0]
	v_xor_b32_e32 v7, v7, v3
	v_floor_f32_e32 v13, v11
	v_cndmask_b32_e32 v36, v204, v12, vcc
	v_floor_f32_e32 v12, v10
	v_sub_f32_e32 v13, v11, v13
	v_sub_f32_e32 v12, v10, v12
	v_min_f32_e32 v13, 0x3f7fffff, v13
	v_cmp_u_f32_e32 vcc, v11, v11
	v_min_f32_e32 v12, 0x3f7fffff, v12
	ds_write_b128 v87, v[34:37] offset:25344
	v_cndmask_b32_e32 v13, v13, v11, vcc
	v_cmp_u_f32_e32 vcc, v10, v10
	v_xor_b32_e32 v6, v6, v2
	s_nop 0
	v_cndmask_b32_e32 v12, v12, v10, vcc
	v_pk_add_f32 v[12:13], v[12:13], v[12:13]
	v_cmp_class_f32_e32 vcc, v10, v239
	s_nop 1
	v_cndmask_b32_e64 v10, v12, 0, vcc
	v_cmp_class_f32_e32 vcc, v11, v239
	s_nop 1
	v_cndmask_b32_e64 v11, v13, 0, vcc
; __device__ __forceinline__ unsigned pk2(float lo, float hi) { unsigned r; asm volatile("v_cvt_pk_bf16_f32 %0, %1, %2" : "=v"(r) : "v"(lo), "v"(hi)); return r; }
; __device__ __forceinline__ void ph_filtergen(KP p, int l, unsigned char* sm, int wv) {
;     ...
;             for (int i = 0; i < 8; ++i) h2[lane * 68 + wid * 8 + i] = sinpif(f2[wid * 8 + i] * a[i] * 0.3183098861837907f);
;         }
;         __syncthreads();
; #pragma unroll 1
;         for (int pass = 0; pass < 4; ++pass) {
;             const int ol = tid & 255, o = pass * 256 + ol, ph0 = (tid >> 8) * 32;
;             float wcol[64];
; #pragma unroll
;             for (int j = 0; j < 64; ++j) wcol[j] = w3[j * 1024 + o];
; #pragma unroll 2
;             for (int pp = 0; pp < 32; ++pp) {
;                 const f32x4* hr = (const f32x4*)(h2 + (ph0 + pp) * 68);
;                 float acc0 = 0.f, acc1 = 0.f;
; #pragma unroll
;                 for (int j4 = 0; j4 < 16; ++j4) { const f32x4 hv = hr[j4]; acc0 += hv.x * wcol[j4 * 4] + hv.z * wcol[j4 * 4 + 2]; acc1 += hv.y * wcol[j4 * 4 + 1] + hv.w * wcol[j4 * 4 + 3]; }
;                 ot[ol * 65 + ph0 + pp] = acc0 + acc1;
;             }
;             __syncthreads();
;             for (int e = tid; e < 256 * 64; e += 512) {
;                 const int ol2 = e >> 6, pos = e & 63, o2 = pass * 256 + ol2, c = o2 & 511, n = n0 + pos;
;                 const float tt = (float)n / (float)(L - 1);
;                 const float delta = fabsf(-3.070113457325394f + (float)c * ((-15.350567286626971f + 3.070113457325394f) / 511.0f));
;                 float val = ot[ol2 * 65 + pos] * __expf(-tt * delta);
;                 bf16_t* kc = kf + (size_t)c * (2 * L);
;                 if (o2 < 512) { if (n == 0) val += hb[c]; kc[n] = (bf16_t)(pk2(val, 0.f) & 0xffffu); }
;                 else { if (n >= 1) kc[2 * L - n] = (bf16_t)(pk2(val, 0.f) & 0xffffu); else kc[L] = (bf16_t)0; }
	v_cndmask_b32_e64 v11, |v3|, v11, s[0:1]
	v_cmp_gt_f32_e64 s[0:1], |v2|, 1.0
	v_add_f32_e32 v13, v11, v11
	v_rndne_f32_e32 v13, v13
	v_cndmask_b32_e64 v10, |v2|, v10, s[0:1]
	v_add_f32_e32 v12, v10, v10
	v_rndne_f32_e32 v12, v12
	v_pk_fma_f32 v[10:11], v[12:13], -0.5, v[10:11] op_sel_hi:[1,0,1]
	v_cvt_i32_f32_e32 v33, v13
	v_cvt_i32_f32_e32 v38, v12
	v_pk_mul_f32 v[12:13], v[10:11], v[10:11]
	v_cmp_gt_f32_e64 s[0:1], |v5|, 1.0
	v_pk_fma_f32 v[34:35], v[12:13], s[36:37], v[14:15] op_sel_hi:[1,0,0]
	v_pk_mul_f32 v[36:37], v[10:11], v[12:13]
	v_pk_fma_f32 v[34:35], v[12:13], v[34:35], s[38:39] op_sel_hi:[1,1,0]
	s_nop 0
	v_pk_fma_f32 v[34:35], v[12:13], v[34:35], s[40:41] op_sel_hi:[1,1,0]
	s_nop 0
	v_pk_mul_f32 v[34:35], v[36:37], v[34:35]
	s_nop 0
	v_pk_fma_f32 v[10:11], v[10:11], s[42:43], v[34:35] op_sel_hi:[1,0,1]
	v_pk_fma_f32 v[34:35], v[12:13], s[44:45], v[16:17] op_sel_hi:[1,0,0]
	s_nop 0
	v_pk_fma_f32 v[34:35], v[12:13], v[34:35], s[46:47] op_sel_hi:[1,1,0]
	s_nop 0
	v_pk_fma_f32 v[34:35], v[12:13], v[34:35], s[48:49] op_sel_hi:[1,1,0]
	s_nop 0
	v_pk_fma_f32 v[34:35], v[12:13], v[34:35], s[50:51] op_sel_hi:[1,1,0]
	s_nop 0
	v_pk_fma_f32 v[12:13], v[12:13], v[34:35], 1.0 op_sel_hi:[1,1,0]
	v_and_b32_e32 v34, 1, v33
	v_and_b32_e32 v35, 1, v38
	v_cmp_eq_u32_e32 vcc, 0, v34
	s_nop 1
	v_cndmask_b32_e32 v11, v13, v11, vcc
	v_cmp_eq_u32_e32 vcc, 0, v35
	v_lshlrev_b32_e32 v13, 30, v38
	v_and_b32_e32 v13, 0x80000000, v13
	v_cndmask_b32_e32 v10, v12, v10, vcc
	v_lshlrev_b32_e32 v12, 30, v33
	v_and_b32_e32 v12, 0x80000000, v12
	v_xor_b32_e32 v7, v7, v12
	v_xor_b32_e32 v6, v6, v13
	v_xor_b32_e32 v7, v7, v11
	v_cmp_class_f32_e32 vcc, v3, v242
	v_xor_b32_e32 v6, v6, v10
	s_nop 0
	v_cndmask_b32_e32 v3, v204, v7, vcc
	v_cmp_class_f32_e32 vcc, v2, v242
	v_and_b32_e32 v7, 0x7fffffff, v5
	s_nop 0
	v_cndmask_b32_e32 v2, v204, v6, vcc
	v_and_b32_e32 v6, 0x7fffffff, v4
	v_pk_mul_f32 v[8:9], v[6:7], 0.5 op_sel_hi:[1,0]
	v_xor_b32_e32 v7, v7, v5
	v_floor_f32_e32 v11, v9
	v_floor_f32_e32 v10, v8
	v_sub_f32_e32 v11, v9, v11
	v_sub_f32_e32 v10, v8, v10
	v_min_f32_e32 v11, 0x3f7fffff, v11
	v_cmp_u_f32_e32 vcc, v9, v9
	v_min_f32_e32 v10, 0x3f7fffff, v10
	v_xor_b32_e32 v6, v6, v4
	v_cndmask_b32_e32 v11, v11, v9, vcc
	v_cmp_u_f32_e32 vcc, v8, v8
	s_nop 1
	v_cndmask_b32_e32 v10, v10, v8, vcc
	v_pk_add_f32 v[10:11], v[10:11], v[10:11]
	v_cmp_class_f32_e32 vcc, v8, v239
	s_nop 1
	v_cndmask_b32_e64 v8, v10, 0, vcc
	v_cmp_class_f32_e32 vcc, v9, v239
	s_nop 1
	v_cndmask_b32_e64 v9, v11, 0, vcc
	v_cndmask_b32_e64 v9, |v5|, v9, s[0:1]
	v_cmp_gt_f32_e64 s[0:1], |v4|, 1.0
	v_add_f32_e32 v11, v9, v9
	v_rndne_f32_e32 v11, v11
	v_cndmask_b32_e64 v8, |v4|, v8, s[0:1]
	v_add_f32_e32 v10, v8, v8
	v_rndne_f32_e32 v10, v10
	v_pk_fma_f32 v[8:9], v[10:11], -0.5, v[8:9] op_sel_hi:[1,0,1]
	v_cvt_i32_f32_e32 v33, v11
	v_cvt_i32_f32_e32 v34, v10
	v_pk_mul_f32 v[10:11], v[8:9], v[8:9]
	s_add_i32 s0, s14, -1
	v_pk_fma_f32 v[12:13], v[10:11], s[36:37], v[14:15] op_sel_hi:[1,0,0]
	v_pk_mul_f32 v[14:15], v[8:9], v[10:11]
	v_pk_fma_f32 v[12:13], v[10:11], v[12:13], s[38:39] op_sel_hi:[1,1,0]
	s_nop 0
	v_pk_fma_f32 v[12:13], v[10:11], v[12:13], s[40:41] op_sel_hi:[1,1,0]
	s_nop 0
	v_pk_mul_f32 v[12:13], v[14:15], v[12:13]
	s_nop 0
	v_pk_fma_f32 v[8:9], v[8:9], s[42:43], v[12:13] op_sel_hi:[1,0,1]
	v_pk_fma_f32 v[12:13], v[10:11], s[44:45], v[16:17] op_sel_hi:[1,0,0]
	s_nop 0
	v_pk_fma_f32 v[12:13], v[10:11], v[12:13], s[46:47] op_sel_hi:[1,1,0]
	s_nop 0
	v_pk_fma_f32 v[12:13], v[10:11], v[12:13], s[48:49] op_sel_hi:[1,1,0]
	s_nop 0
	v_pk_fma_f32 v[12:13], v[10:11], v[12:13], s[50:51] op_sel_hi:[1,1,0]
	s_nop 0
	v_pk_fma_f32 v[10:11], v[10:11], v[12:13], 1.0 op_sel_hi:[1,1,0]
	v_and_b32_e32 v12, 1, v33
	v_and_b32_e32 v13, 1, v34
	v_cmp_eq_u32_e32 vcc, 0, v12
	s_nop 1
	v_cndmask_b32_e32 v9, v11, v9, vcc
	v_cmp_eq_u32_e32 vcc, 0, v13
	v_lshlrev_b32_e32 v11, 30, v34
	v_and_b32_e32 v11, 0x80000000, v11
	v_cndmask_b32_e32 v8, v10, v8, vcc
	v_lshlrev_b32_e32 v10, 30, v33
	v_and_b32_e32 v10, 0x80000000, v10
	v_xor_b32_e32 v7, v7, v10
	v_xor_b32_e32 v6, v6, v11
	v_xor_b32_e32 v7, v7, v9
	v_cmp_class_f32_e32 vcc, v5, v242
	v_xor_b32_e32 v6, v6, v8
	v_ashrrev_i32_e32 v33, 31, v32
	v_cndmask_b32_e32 v5, v204, v7, vcc
	v_cmp_class_f32_e32 vcc, v4, v242
	s_nop 1
	v_cndmask_b32_e32 v4, v204, v6, vcc
	ds_write_b128 v87, v[2:5] offset:25360
	v_cvt_f32_u32_e32 v2, s0
	s_and_b64 s[0:1], s[8:9], exec
	s_cselect_b32 s42, 15, 14
	v_cmp_eq_u32_e64 s[8:9], 0, v32
	v_div_scale_f32 v3, s[0:1], v2, v2, -v0
	v_rcp_f32_e32 v4, v3
	v_cmp_lt_i32_e64 s[0:1], 0, v32
	s_waitcnt lgkmcnt(0)
	s_barrier
	v_fma_f32 v5, -v3, v4, 1.0
	v_fmac_f32_e32 v4, v5, v4
	v_div_scale_f32 v5, vcc, -v0, v2, -v0
	v_mul_f32_e32 v6, v5, v4
	v_fma_f32 v7, -v3, v6, v5
	v_fmac_f32_e32 v6, v7, v4
	v_fma_f32 v3, -v3, v6, v5
	v_div_fmas_f32 v3, v3, v4, v6
	v_div_fixup_f32 v94, v3, v2, -v0
	v_sub_u32_e32 v2, s18, v32
	v_ashrrev_i32_e32 v3, 31, v2
	s_branch .LBB0_892

; __device__ __forceinline__ void ph_filtergen(KP p, int l, unsigned char* sm, int wv) {
;     ...
;         for (int pass = 0; pass < 4; ++pass) {
;             const int ol = tid & 255, o = pass * 256 + ol, ph0 = (tid >> 8) * 32;
;             float wcol[64];
; #pragma unroll
;             for (int j = 0; j < 64; ++j) wcol[j] = w3[j * 1024 + o];
; #pragma unroll 2
;             for (int pp = 0; pp < 32; ++pp) {
;                 const f32x4* hr = (const f32x4*)(h2 + (ph0 + pp) * 68);
;                 float acc0 = 0.f, acc1 = 0.f;
; #pragma unroll
;                 for (int j4 = 0; j4 < 16; ++j4) { const f32x4 hv = hr[j4]; acc0 += hv.x * wcol[j4 * 4] + hv.z * wcol[j4 * 4 + 2]; acc1 += hv.y * wcol[j4 * 4 + 1] + hv.w * wcol[j4 * 4 + 3]; }
.LBB0_892:
	s_lshl_b32 s43, s31, 8
	v_lshrrev_b32_e32 v95, 6, v18
	v_lshrrev_b32_e32 v210, 5, v19
	v_and_b32_e32 v211, 31, v19
	v_lshl_add_u32 v212, v95, 5, v211
	v_add_u32_e32 v212, s43, v212
	v_lshl_add_u32 v212, v210, 15, v212
	v_lshlrev_b32_e32 v212, 2, v212
	s_mov_b64 s[98:99], s[2:3]
	global_load_dword v176, v212, s[98:99]
	s_add_u32 s98, s98, 0x1000
	s_addc_u32 s99, s99, 0
	global_load_dword v177, v212, s[98:99]
	s_add_u32 s98, s98, 0x1000
	s_addc_u32 s99, s99, 0
	global_load_dword v178, v212, s[98:99]
	s_add_u32 s98, s98, 0x1000
	s_addc_u32 s99, s99, 0
	global_load_dword v179, v212, s[98:99]
	s_add_u32 s98, s98, 0x1000
	s_addc_u32 s99, s99, 0
	global_load_dword v180, v212, s[98:99]
	s_add_u32 s98, s98, 0x1000
	s_addc_u32 s99, s99, 0
	global_load_dword v181, v212, s[98:99]
	s_add_u32 s98, s98, 0x1000
	s_addc_u32 s99, s99, 0
	global_load_dword v182, v212, s[98:99]
	s_add_u32 s98, s98, 0x1000
	s_addc_u32 s99, s99, 0
	global_load_dword v183, v212, s[98:99]
	s_add_u32 s98, s98, 0x1000
	s_addc_u32 s99, s99, 0
	global_load_dword v184, v212, s[98:99]
	s_add_u32 s98, s98, 0x1000
	s_addc_u32 s99, s99, 0
	global_load_dword v185, v212, s[98:99]
	s_add_u32 s98, s98, 0x1000
	s_addc_u32 s99, s99, 0
	global_load_dword v186, v212, s[98:99]
	s_add_u32 s98, s98, 0x1000
	s_addc_u32 s99, s99, 0
	global_load_dword v187, v212, s[98:99]
	s_add_u32 s98, s98, 0x1000
	s_addc_u32 s99, s99, 0
	global_load_dword v188, v212, s[98:99]
	s_add_u32 s98, s98, 0x1000
	s_addc_u32 s99, s99, 0
	global_load_dword v189, v212, s[98:99]
	s_add_u32 s98, s98, 0x1000
	s_addc_u32 s99, s99, 0
	global_load_dword v190, v212, s[98:99]
	s_add_u32 s98, s98, 0x1000
	s_addc_u32 s99, s99, 0
	global_load_dword v191, v212, s[98:99]
	s_add_u32 s98, s98, 0x1000
	s_addc_u32 s99, s99, 0
	global_load_dword v192, v212, s[98:99]
	s_add_u32 s98, s98, 0x1000
	s_addc_u32 s99, s99, 0
	global_load_dword v193, v212, s[98:99]
	s_add_u32 s98, s98, 0x1000
	s_addc_u32 s99, s99, 0
	global_load_dword v194, v212, s[98:99]
	s_add_u32 s98, s98, 0x1000
	s_addc_u32 s99, s99, 0
	global_load_dword v195, v212, s[98:99]
	s_add_u32 s98, s98, 0x1000
	s_addc_u32 s99, s99, 0
	global_load_dword v196, v212, s[98:99]
	s_add_u32 s98, s98, 0x1000
	s_addc_u32 s99, s99, 0
	global_load_dword v197, v212, s[98:99]
	s_add_u32 s98, s98, 0x1000
	s_addc_u32 s99, s99, 0
	global_load_dword v198, v212, s[98:99]
	s_add_u32 s98, s98, 0x1000
	s_addc_u32 s99, s99, 0
	global_load_dword v199, v212, s[98:99]
	s_add_u32 s98, s98, 0x1000
	s_addc_u32 s99, s99, 0
	global_load_dword v200, v212, s[98:99]
	s_add_u32 s98, s98, 0x1000
	s_addc_u32 s99, s99, 0
	global_load_dword v201, v212, s[98:99]
	s_add_u32 s98, s98, 0x1000
	s_addc_u32 s99, s99, 0
	global_load_dword v202, v212, s[98:99]
	s_add_u32 s98, s98, 0x1000
	s_addc_u32 s99, s99, 0
	global_load_dword v203, v212, s[98:99]
	s_add_u32 s98, s98, 0x1000
	s_addc_u32 s99, s99, 0
	global_load_dword v206, v212, s[98:99]
	s_add_u32 s98, s98, 0x1000
	s_addc_u32 s99, s99, 0
	global_load_dword v207, v212, s[98:99]
	s_add_u32 s98, s98, 0x1000
	s_addc_u32 s99, s99, 0
	global_load_dword v208, v212, s[98:99]
	s_add_u32 s98, s98, 0x1000
	s_addc_u32 s99, s99, 0
	global_load_dword v209, v212, s[98:99]
	v_mul_u32_u24_e32 v213, 0x110, v211
	v_lshl_add_u32 v213, v210, 7, v213
	v_add_u32_e32 v213, 0x6300, v213
	v_lshlrev_b32_e32 v214, 5, v95
	v_lshl_add_u32 v214, v210, 2, v214
	v_mul_u32_u24_e32 v214, 0x104, v214
	v_lshl_add_u32 v214, v211, 2, v214
	v_add_u32_e32 v214, 0x10800, v214
	ds_read_b128 v[96:99], v213 offset:0
	ds_read_b128 v[100:103], v213 offset:16
	ds_read_b128 v[104:107], v213 offset:32
	ds_read_b128 v[108:111], v213 offset:48
	ds_read_b128 v[112:115], v213 offset:64
	ds_read_b128 v[116:119], v213 offset:80
	ds_read_b128 v[120:123], v213 offset:96
	ds_read_b128 v[124:127], v213 offset:112
	s_waitcnt vmcnt(0) lgkmcnt(0)
; __device__ __forceinline__ void ph_filtergen(KP p, int l, unsigned char* sm, int wv) {
;     ...
;             for (int pp = 0; pp < 32; ++pp) {
;                 const f32x4* hr = (const f32x4*)(h2 + (ph0 + pp) * 68);
;                 float acc0 = 0.f, acc1 = 0.f;
; #pragma unroll
;                 for (int j4 = 0; j4 < 16; ++j4) { const f32x4 hv = hr[j4]; acc0 += hv.x * wcol[j4 * 4] + hv.z * wcol[j4 * 4 + 2]; acc1 += hv.y * wcol[j4 * 4 + 1] + hv.w * wcol[j4 * 4 + 3]; }
;                 ot[ol * 65 + ph0 + pp] = acc0 + acc1;
;             }
;             __syncthreads();
	v_mfma_f32_32x32x2_f32 v[128:143], v176, v96, 0
	v_mfma_f32_32x32x2_f32 v[128:143], v177, v97, v[128:143]
	v_mfma_f32_32x32x2_f32 v[128:143], v178, v98, v[128:143]
	v_mfma_f32_32x32x2_f32 v[128:143], v179, v99, v[128:143]
	v_mfma_f32_32x32x2_f32 v[128:143], v180, v100, v[128:143]
	v_mfma_f32_32x32x2_f32 v[128:143], v181, v101, v[128:143]
	v_mfma_f32_32x32x2_f32 v[128:143], v182, v102, v[128:143]
	v_mfma_f32_32x32x2_f32 v[128:143], v183, v103, v[128:143]
	v_mfma_f32_32x32x2_f32 v[128:143], v184, v104, v[128:143]
	v_mfma_f32_32x32x2_f32 v[128:143], v185, v105, v[128:143]
	v_mfma_f32_32x32x2_f32 v[128:143], v186, v106, v[128:143]
	v_mfma_f32_32x32x2_f32 v[128:143], v187, v107, v[128:143]
	v_mfma_f32_32x32x2_f32 v[128:143], v188, v108, v[128:143]
	v_mfma_f32_32x32x2_f32 v[128:143], v189, v109, v[128:143]
	v_mfma_f32_32x32x2_f32 v[128:143], v190, v110, v[128:143]
	v_mfma_f32_32x32x2_f32 v[128:143], v191, v111, v[128:143]
	v_mfma_f32_32x32x2_f32 v[128:143], v192, v112, v[128:143]
	v_mfma_f32_32x32x2_f32 v[128:143], v193, v113, v[128:143]
	v_mfma_f32_32x32x2_f32 v[128:143], v194, v114, v[128:143]
	v_mfma_f32_32x32x2_f32 v[128:143], v195, v115, v[128:143]
	v_mfma_f32_32x32x2_f32 v[128:143], v196, v116, v[128:143]
	v_mfma_f32_32x32x2_f32 v[128:143], v197, v117, v[128:143]
	v_mfma_f32_32x32x2_f32 v[128:143], v198, v118, v[128:143]
	v_mfma_f32_32x32x2_f32 v[128:143], v199, v119, v[128:143]
	v_mfma_f32_32x32x2_f32 v[128:143], v200, v120, v[128:143]
	v_mfma_f32_32x32x2_f32 v[128:143], v201, v121, v[128:143]
	v_mfma_f32_32x32x2_f32 v[128:143], v202, v122, v[128:143]
	v_mfma_f32_32x32x2_f32 v[128:143], v203, v123, v[128:143]
	v_mfma_f32_32x32x2_f32 v[128:143], v206, v124, v[128:143]
	v_mfma_f32_32x32x2_f32 v[128:143], v207, v125, v[128:143]
	v_mfma_f32_32x32x2_f32 v[128:143], v208, v126, v[128:143]
	v_mfma_f32_32x32x2_f32 v[128:143], v209, v127, v[128:143]
	s_nop 15
	s_nop 3
	ds_write_b32 v214, v128 offset:0
	ds_write_b32 v214, v129 offset:260
	ds_write_b32 v214, v130 offset:520
	ds_write_b32 v214, v131 offset:780
	ds_write_b32 v214, v132 offset:2080
	ds_write_b32 v214, v133 offset:2340
	ds_write_b32 v214, v134 offset:2600
	ds_write_b32 v214, v135 offset:2860
	ds_write_b32 v214, v136 offset:4160
	ds_write_b32 v214, v137 offset:4420
	ds_write_b32 v214, v138 offset:4680
	ds_write_b32 v214, v139 offset:4940
	ds_write_b32 v214, v140 offset:6240
	ds_write_b32 v214, v141 offset:6500
	ds_write_b32 v214, v142 offset:6760
	ds_write_b32 v214, v143 offset:7020
	ds_read_b128 v[96:99], v213 offset:8704
	ds_read_b128 v[100:103], v213 offset:8720
	ds_read_b128 v[104:107], v213 offset:8736
	ds_read_b128 v[108:111], v213 offset:8752
	ds_read_b128 v[112:115], v213 offset:8768
	ds_read_b128 v[116:119], v213 offset:8784
	ds_read_b128 v[120:123], v213 offset:8800
	ds_read_b128 v[124:127], v213 offset:8816
	s_waitcnt lgkmcnt(0)
	v_mfma_f32_32x32x2_f32 v[128:143], v176, v96, 0
	v_mfma_f32_32x32x2_f32 v[128:143], v177, v97, v[128:143]
	v_mfma_f32_32x32x2_f32 v[128:143], v178, v98, v[128:143]
	v_mfma_f32_32x32x2_f32 v[128:143], v179, v99, v[128:143]
	v_mfma_f32_32x32x2_f32 v[128:143], v180, v100, v[128:143]
	v_mfma_f32_32x32x2_f32 v[128:143], v181, v101, v[128:143]
	v_mfma_f32_32x32x2_f32 v[128:143], v182, v102, v[128:143]
	v_mfma_f32_32x32x2_f32 v[128:143], v183, v103, v[128:143]
	v_mfma_f32_32x32x2_f32 v[128:143], v184, v104, v[128:143]
	v_mfma_f32_32x32x2_f32 v[128:143], v185, v105, v[128:143]
	v_mfma_f32_32x32x2_f32 v[128:143], v186, v106, v[128:143]
	v_mfma_f32_32x32x2_f32 v[128:143], v187, v107, v[128:143]
	v_mfma_f32_32x32x2_f32 v[128:143], v188, v108, v[128:143]
	v_mfma_f32_32x32x2_f32 v[128:143], v189, v109, v[128:143]
	v_mfma_f32_32x32x2_f32 v[128:143], v190, v110, v[128:143]
	v_mfma_f32_32x32x2_f32 v[128:143], v191, v111, v[128:143]
	v_mfma_f32_32x32x2_f32 v[128:143], v192, v112, v[128:143]
	v_mfma_f32_32x32x2_f32 v[128:143], v193, v113, v[128:143]
	v_mfma_f32_32x32x2_f32 v[128:143], v194, v114, v[128:143]
	v_mfma_f32_32x32x2_f32 v[128:143], v195, v115, v[128:143]
	v_mfma_f32_32x32x2_f32 v[128:143], v196, v116, v[128:143]
	v_mfma_f32_32x32x2_f32 v[128:143], v197, v117, v[128:143]
	v_mfma_f32_32x32x2_f32 v[128:143], v198, v118, v[128:143]
	v_mfma_f32_32x32x2_f32 v[128:143], v199, v119, v[128:143]
	v_mfma_f32_32x32x2_f32 v[128:143], v200, v120, v[128:143]
	v_mfma_f32_32x32x2_f32 v[128:143], v201, v121, v[128:143]
	v_mfma_f32_32x32x2_f32 v[128:143], v202, v122, v[128:143]
	v_mfma_f32_32x32x2_f32 v[128:143], v203, v123, v[128:143]
	v_mfma_f32_32x32x2_f32 v[128:143], v206, v124, v[128:143]
	v_mfma_f32_32x32x2_f32 v[128:143], v207, v125, v[128:143]
	v_mfma_f32_32x32x2_f32 v[128:143], v208, v126, v[128:143]
	v_mfma_f32_32x32x2_f32 v[128:143], v209, v127, v[128:143]
	s_nop 15
	s_nop 3
	ds_write_b32 v214, v128 offset:128
	ds_write_b32 v214, v129 offset:388
	ds_write_b32 v214, v130 offset:648
	ds_write_b32 v214, v131 offset:908
	ds_write_b32 v214, v132 offset:2208
	ds_write_b32 v214, v133 offset:2468
	ds_write_b32 v214, v134 offset:2728
	ds_write_b32 v214, v135 offset:2988
	ds_write_b32 v214, v136 offset:4288
	ds_write_b32 v214, v137 offset:4548
	ds_write_b32 v214, v138 offset:4808
	ds_write_b32 v214, v139 offset:5068
	ds_write_b32 v214, v140 offset:6368
	ds_write_b32 v214, v141 offset:6628
	ds_write_b32 v214, v142 offset:6888
	ds_write_b32 v214, v143 offset:7148
	s_waitcnt lgkmcnt(0)
	s_barrier
	s_and_saveexec_b64 s[18:19], s[6:7]
	s_cbranch_execz .LBB0_891
	s_mov_b64 s[36:37], 0
	v_mov_b32_e32 v6, v18
	s_branch .LBB0_898
